# v26 + moba_bucket tile loop: K / V^T load addresses use per-thread offsets computed once per phase with scalar-base loads; 57 address VALU ops per tile removed
# baseline (speedup 1.0000x reference)
.LBB0_1448:
	s_or_b64 exec, exec, s[0:1]
	v_readlane_b32 s0, v237, 56
	v_readlane_b32 s1, v237, 57
	s_add_u32 s0, s0, 0x3d00100
	s_waitcnt lgkmcnt(0)
	v_mov_b32_e32 v0, v128
	s_barrier
	v_and_b32_e32 v254, 7, v128
	v_lshlrev_b32_e32 v254, 4, v254
	v_add_u32_e32 v255, 0x0, v128
	v_lshrrev_b32_e32 v238, 5, v255
	v_lshlrev_b32_e32 v238, 15, v238
	v_and_b32_e32 v180, 31, v255
	v_lshl_add_u32 v238, v180, 4, v238
	v_lshrrev_b32_e32 v246, 3, v255
	v_mul_u32_u24_e32 v246, 0xc00, v246
	v_add_u32_e32 v246, v246, v254
	v_add_u32_e32 v255, 0x100, v128
	v_lshrrev_b32_e32 v239, 5, v255
	v_lshlrev_b32_e32 v239, 15, v239
	v_and_b32_e32 v180, 31, v255
	v_lshl_add_u32 v239, v180, 4, v239
	v_lshrrev_b32_e32 v247, 3, v255
	v_mul_u32_u24_e32 v247, 0xc00, v247
	v_add_u32_e32 v247, v247, v254
	v_add_u32_e32 v255, 0x200, v128
	v_lshrrev_b32_e32 v240, 5, v255
	v_lshlrev_b32_e32 v240, 15, v240
	v_and_b32_e32 v180, 31, v255
	v_lshl_add_u32 v240, v180, 4, v240
	v_lshrrev_b32_e32 v248, 3, v255
	v_mul_u32_u24_e32 v248, 0xc00, v248
	v_add_u32_e32 v248, v248, v254
	v_add_u32_e32 v255, 0x300, v128
	v_lshrrev_b32_e32 v241, 5, v255
	v_lshlrev_b32_e32 v241, 15, v241
	v_and_b32_e32 v180, 31, v255
	v_lshl_add_u32 v241, v180, 4, v241
	v_lshrrev_b32_e32 v249, 3, v255
	v_mul_u32_u24_e32 v249, 0xc00, v249
	v_add_u32_e32 v249, v249, v254
	v_add_u32_e32 v255, 0x400, v128
	v_lshrrev_b32_e32 v242, 5, v255
	v_lshlrev_b32_e32 v242, 15, v242
	v_and_b32_e32 v180, 31, v255
	v_lshl_add_u32 v242, v180, 4, v242
	v_lshrrev_b32_e32 v250, 3, v255
	v_mul_u32_u24_e32 v250, 0xc00, v250
	v_add_u32_e32 v250, v250, v254
	v_add_u32_e32 v255, 0x500, v128
	v_lshrrev_b32_e32 v243, 5, v255
	v_lshlrev_b32_e32 v243, 15, v243
	v_and_b32_e32 v180, 31, v255
	v_lshl_add_u32 v243, v180, 4, v243
	v_lshrrev_b32_e32 v251, 3, v255
	v_mul_u32_u24_e32 v251, 0xc00, v251
	v_add_u32_e32 v251, v251, v254
	v_add_u32_e32 v255, 0x600, v128
	v_lshrrev_b32_e32 v244, 5, v255
	v_lshlrev_b32_e32 v244, 15, v244
	v_and_b32_e32 v180, 31, v255
	v_lshl_add_u32 v244, v180, 4, v244
	v_lshrrev_b32_e32 v252, 3, v255
	v_mul_u32_u24_e32 v252, 0xc00, v252
	v_add_u32_e32 v252, v252, v254
	v_add_u32_e32 v255, 0x700, v128
	v_lshrrev_b32_e32 v245, 5, v255
	v_lshlrev_b32_e32 v245, 15, v245
	v_and_b32_e32 v180, 31, v255
	v_lshl_add_u32 v245, v180, 4, v245
	v_lshrrev_b32_e32 v253, 3, v255
	v_mul_u32_u24_e32 v253, 0xc00, v253
	v_add_u32_e32 v253, v253, v254
	s_addc_u32 s1, s1, 0
	v_readlane_b32 s2, v237, 58
	v_ashrrev_i32_e32 v1, 31, v0
	v_lshl_add_u64 v[2:3], v[0:1], 2, s[0:1]
	global_load_dword v2, v[2:3], off
	v_mov_b32_e32 v1, 0x12c00
	v_lshl_add_u32 v1, v0, 2, v1
	s_barrier
	v_readlane_b32 s3, v237, 59
	v_cmp_lt_i32_e32 vcc, 0, v0
	s_waitcnt vmcnt(0)
	v_add_u32_e32 v2, 63, v2
	v_ashrrev_i32_e32 v2, 6, v2
	ds_write_b32 v1, v2
	s_waitcnt lgkmcnt(0)
	s_barrier
	ds_read_b32 v2, v1
	s_and_saveexec_b64 s[2:3], vcc
	s_cbranch_execz .LBB0_1450
	v_add_u32_e32 v3, -4, v1
	ds_read_b32 v3, v3
	s_waitcnt lgkmcnt(0)
	v_add_u32_e32 v2, v3, v2

.LBB0_1474:
	s_ashr_i32 s12, s14, 7
	s_ashr_i32 s13, s12, 31
	v_ashrrev_i32_e32 v40, 4, v53
	s_lshl_b64 s[22:23], s[12:13], 14
	v_ashrrev_i32_e32 v41, 31, v40
	v_lshl_add_u64 v[0:1], s[22:23], 0, v[40:41]
	s_bfe_u32 s11, s14, 0x10006
	v_mad_u64_u32 v[2:3], s[24:25], v0, s16, v[38:39]
	s_lshl_b32 s14, s14, 8
	s_and_b32 s24, s14, 0x3f00
	s_or_b32 s14, s22, s24
	s_mul_i32 s15, s23, 0xc00
	s_mul_hi_u32 s22, s14, 0xc00
	s_add_i32 s22, s22, s15
	s_mulk_i32 s14, 0xc00
	s_add_u32 s14, s76, s14
	s_addc_u32 s15, s77, s22
	s_lshl_b32 s22, s11, 7
	v_lshlrev_b32_e32 v0, 5, v53
	s_add_u32 s22, s14, s22
	v_and_b32_e32 v0, 0x180, v0
	s_addc_u32 s23, s15, 0
	s_mov_b64 s[100:101], s[22:23]
	s_lshl_b32 s14, s12, 1
	v_mad_i32_i24 v3, v1, s16, v3
	v_lshl_or_b32 v36, s11, 9, v0
	s_or_b32 s14, s14, s11
	v_mov_b32_e32 v58, v128
	v_lshl_add_u64 v[88:89], v[2:3], 0, v[36:37]
	s_add_i32 s14, s14, 4
	s_ashr_i32 s15, s14, 31
	v_lshlrev_b32_e32 v2, 4, v58
	v_add_u32_e32 v12, 0x100, v58
	v_and_b32_e32 v36, 0x70, v2
	v_ashrrev_i32_e32 v2, 31, v58
	v_ashrrev_i32_e32 v10, 31, v12
	v_add_u32_e32 v57, 0x400, v58
	s_lshl_b64 s[14:15], s[14:15], 21
	v_lshrrev_b32_e32 v2, 27, v2
	v_lshrrev_b32_e32 v10, 27, v10
	v_ashrrev_i32_e32 v34, 31, v57
	s_add_u32 s14, s80, s14
	v_add_u32_e32 v2, v58, v2
	v_add_u32_e32 v10, v12, v10
	v_lshrrev_b32_e32 v34, 27, v34
	s_addc_u32 s15, s81, s15
	s_lshl_b32 s24, s24, 1
	v_ashrrev_i32_e32 v96, 5, v2
	v_ashrrev_i32_e32 v100, 5, v10
	v_add_u32_e32 v34, v57, v34
	s_add_u32 s14, s14, s24
	v_lshlrev_b32_e32 v4, 3, v58
	v_lshlrev_b32_e32 v5, 8, v96
	v_ashrrev_i32_e32 v112, 5, v34
	s_addc_u32 s15, s15, 0
	v_ashrrev_i32_e32 v44, 3, v58
	v_sub_u32_e32 v98, v4, v5
	v_add_u32_e32 v20, 0x200, v58
	v_ashrrev_i32_e32 v101, 3, v57
	v_lshlrev_b32_e32 v60, 8, v112
	v_lshlrev_b32_e32 v57, 3, v57
	v_ashrrev_i32_e32 v18, 31, v20
	v_sub_u32_e32 v114, v57, v60
	v_add_u32_e32 v57, 0x500, v58
	v_ashrrev_i32_e32 v59, 3, v12
	v_lshlrev_b32_e32 v13, 8, v100
	v_lshlrev_b32_e32 v12, 3, v12
	v_lshrrev_b32_e32 v18, 27, v18
	v_ashrrev_i32_e32 v66, 31, v57
	global_load_dwordx4 v[0:3], v246, s[100:101] offset:2560
	s_nop 0
	global_load_dwordx4 v[4:7], v238, s[14:15]
	v_sub_u32_e32 v102, v12, v13
	v_add_u32_e32 v18, v20, v18
	v_add_u32_e32 v28, 0x300, v58
	v_lshrrev_b32_e32 v66, 27, v66
	v_ashrrev_i32_e32 v104, 5, v18
	v_ashrrev_i32_e32 v26, 31, v28
	v_add_u32_e32 v66, v57, v66
	v_ashrrev_i32_e32 v97, 3, v20
	v_lshlrev_b32_e32 v21, 8, v104
	v_lshlrev_b32_e32 v20, 3, v20
	v_lshrrev_b32_e32 v26, 27, v26
	v_ashrrev_i32_e32 v116, 5, v66
	global_load_dwordx4 v[8:11], v247, s[100:101] offset:2560
	s_nop 0
	global_load_dwordx4 v[12:15], v239, s[14:15]
	v_sub_u32_e32 v106, v20, v21
	v_add_u32_e32 v26, v28, v26
	v_ashrrev_i32_e32 v103, 3, v57
	v_lshlrev_b32_e32 v68, 8, v116
	v_lshlrev_b32_e32 v57, 3, v57
	s_waitcnt lgkmcnt(0)
	v_ashrrev_i32_e32 v108, 5, v26
	v_sub_u32_e32 v118, v57, v68
	v_add_u32_e32 v57, 0x600, v58
	v_ashrrev_i32_e32 v99, 3, v28
	v_lshlrev_b32_e32 v29, 8, v108
	v_lshlrev_b32_e32 v28, 3, v28
	v_ashrrev_i32_e32 v74, 31, v57
	global_load_dwordx4 v[16:19], v248, s[100:101] offset:2560
	s_nop 0
	global_load_dwordx4 v[20:23], v240, s[14:15]
	v_sub_u32_e32 v110, v28, v29
	v_lshrrev_b32_e32 v74, 27, v74
	v_add_u32_e32 v74, v57, v74
	v_ashrrev_i32_e32 v120, 5, v74
	global_load_dwordx4 v[24:27], v249, s[100:101] offset:2560
	s_nop 0
	global_load_dwordx4 v[28:31], v241, s[14:15]
	v_ashrrev_i32_e32 v105, 3, v57
	v_lshlrev_b32_e32 v76, 8, v120
	v_lshlrev_b32_e32 v57, 3, v57
	v_sub_u32_e32 v122, v57, v76
	v_add_u32_e32 v57, 0x700, v58
	v_ashrrev_i32_e32 v107, 3, v57
	global_load_dwordx4 v[32:35], v250, s[100:101] offset:2560
	s_nop 0
	global_load_dwordx4 v[60:63], v242, s[14:15]
	global_load_dwordx4 v[64:67], v251, s[100:101] offset:2560
	s_nop 0
	global_load_dwordx4 v[68:71], v243, s[14:15]
	s_nop 0
	global_load_dwordx4 v[72:75], v252, s[100:101] offset:2560
	s_nop 0
	global_load_dwordx4 v[76:79], v244, s[14:15]
	v_cmp_lt_i32_e32 vcc, v49, v50
	global_load_dwordx4 v[80:83], v253, s[100:101] offset:2560
	v_ashrrev_i32_e32 v42, 31, v57
	v_lshrrev_b32_e32 v42, 27, v42
	v_add_u32_e32 v42, v57, v42
	v_ashrrev_i32_e32 v124, 5, v42
	v_lshlrev_b32_e32 v84, 8, v124
	v_lshlrev_b32_e32 v57, 3, v57
	v_sub_u32_e32 v126, v57, v84
	global_load_dwordx4 v[84:87], v245, s[14:15]
	v_bfe_u32 v57, v58, 4, 2
	v_lshlrev_b32_e32 v42, 4, v57
	v_mov_b32_e32 v43, v37
	v_lshl_add_u64 v[92:93], v[88:89], 0, v[42:43]
	global_load_dwordx4 v[88:91], v[92:93], off offset:1536
	s_nop 0
	global_load_dwordx4 v[92:95], v[92:93], off offset:1600
	v_mad_u64_u32 v[130:131], s[14:15], v44, s17, v[36:37]
	s_barrier
	s_waitcnt vmcnt(17)
	ds_write_b128 v130, v[0:3]
	v_mul_lo_u32 v0, v96, s18
	v_lshl_add_u32 v0, v98, 1, v0
	s_waitcnt vmcnt(16)
	ds_write_b128 v0, v[4:7] offset:40960
	v_mad_u64_u32 v[0:1], s[14:15], v59, s17, v[36:37]
	s_waitcnt vmcnt(15)
	ds_write_b128 v0, v[8:11]
	v_mul_lo_u32 v0, v100, s18
	v_lshl_add_u32 v0, v102, 1, v0
	s_waitcnt vmcnt(14)
	ds_write_b128 v0, v[12:15] offset:40960
	v_mad_u64_u32 v[0:1], s[14:15], v97, s17, v[36:37]
	s_waitcnt vmcnt(13)
	ds_write_b128 v0, v[16:19]
	v_mul_lo_u32 v0, v104, s18
	v_lshl_add_u32 v0, v106, 1, v0
	s_waitcnt vmcnt(12)
	ds_write_b128 v0, v[20:23] offset:40960
	v_mad_u64_u32 v[0:1], s[14:15], v99, s17, v[36:37]
	s_waitcnt vmcnt(11)
	ds_write_b128 v0, v[24:27]
	v_mul_lo_u32 v0, v108, s18
	v_lshl_add_u32 v0, v110, 1, v0
	s_waitcnt vmcnt(10)
	ds_write_b128 v0, v[28:31] offset:40960
	v_mad_u64_u32 v[0:1], s[14:15], v101, s17, v[36:37]
	v_and_b32_e32 v43, 15, v58
	s_waitcnt vmcnt(9)
	ds_write_b128 v0, v[32:35]
	v_mul_lo_u32 v0, v112, s18
	v_lshl_add_u32 v0, v114, 1, v0
	s_waitcnt vmcnt(8)
	ds_write_b128 v0, v[60:63] offset:40960
	v_mad_u64_u32 v[0:1], s[14:15], v103, s17, v[36:37]
	s_waitcnt vmcnt(7)
	ds_write_b128 v0, v[64:67]
	v_mul_lo_u32 v0, v116, s18
	v_lshl_add_u32 v0, v118, 1, v0
	s_waitcnt vmcnt(6)
	ds_write_b128 v0, v[68:71] offset:40960
	v_mad_u64_u32 v[0:1], s[14:15], v105, s17, v[36:37]
	s_waitcnt vmcnt(5)
	ds_write_b128 v0, v[72:75]
	v_mul_lo_u32 v0, v120, s18
	v_lshl_add_u32 v0, v122, 1, v0
	s_waitcnt vmcnt(4)
	ds_write_b128 v0, v[76:79] offset:40960
	v_mad_u64_u32 v[0:1], s[14:15], v107, s17, v[36:37]
	s_waitcnt vmcnt(3)
	ds_write_b128 v0, v[80:83]
	v_mul_lo_u32 v0, v124, s18
	v_lshl_add_u32 v0, v126, 1, v0
	v_mad_u32_u24 v36, v43, s17, v42
	v_mad_u32_u24 v42, v43, s18, v42
	s_waitcnt vmcnt(2)
	ds_write_b128 v0, v[84:87] offset:40960
	s_waitcnt lgkmcnt(0)
	s_barrier
	ds_read_b128 v[156:159], v36
	ds_read_b128 v[160:163], v36 offset:64
	ds_read_b128 v[164:167], v36 offset:2560
	ds_read_b128 v[168:171], v36 offset:2624
	ds_read_b128 v[172:175], v36 offset:5120
	s_waitcnt vmcnt(1)
	s_waitcnt lgkmcnt(4)
	v_mfma_f32_16x16x32_bf16 v[0:3], v[156:159], v[88:91], 0
	ds_read_b128 v[176:179], v36 offset:5184
	s_waitcnt vmcnt(0)
	s_waitcnt lgkmcnt(4)
	v_mfma_f32_16x16x32_bf16 v[60:63], v[160:163], v[92:95], v[0:3]
	ds_read_b128 v[156:159], v36 offset:7680
	s_waitcnt lgkmcnt(4)
	v_mfma_f32_16x16x32_bf16 v[4:7], v[164:167], v[88:91], 0
	ds_read_b128 v[160:163], v36 offset:7744
	s_waitcnt lgkmcnt(4)
	v_mfma_f32_16x16x32_bf16 v[64:67], v[168:171], v[92:95], v[4:7]
	ds_read_b128 v[164:167], v36 offset:10240
	s_waitcnt lgkmcnt(4)
	v_mfma_f32_16x16x32_bf16 v[4:7], v[172:175], v[88:91], 0
	ds_read_b128 v[168:171], v36 offset:10304
	s_waitcnt lgkmcnt(4)
	v_mfma_f32_16x16x32_bf16 v[68:71], v[176:179], v[92:95], v[4:7]
	ds_read_b128 v[172:175], v36 offset:12800
	s_waitcnt lgkmcnt(4)
	v_mfma_f32_16x16x32_bf16 v[4:7], v[156:159], v[88:91], 0
	ds_read_b128 v[176:179], v36 offset:12864
	s_waitcnt lgkmcnt(4)
	v_mfma_f32_16x16x32_bf16 v[72:75], v[160:163], v[92:95], v[4:7]
	ds_read_b128 v[156:159], v36 offset:15360
	s_waitcnt lgkmcnt(4)
	v_mfma_f32_16x16x32_bf16 v[4:7], v[164:167], v[88:91], 0
	ds_read_b128 v[160:163], v36 offset:15424
	s_waitcnt lgkmcnt(4)
	v_mfma_f32_16x16x32_bf16 v[76:79], v[168:171], v[92:95], v[4:7]
	ds_read_b128 v[164:167], v36 offset:17920
	s_waitcnt lgkmcnt(4)
	v_mfma_f32_16x16x32_bf16 v[4:7], v[172:175], v[88:91], 0
	ds_read_b128 v[168:171], v36 offset:17984
	s_waitcnt lgkmcnt(4)
	v_mfma_f32_16x16x32_bf16 v[80:83], v[176:179], v[92:95], v[4:7]
	ds_read_b128 v[172:175], v36 offset:20480
	s_waitcnt lgkmcnt(4)
	v_mfma_f32_16x16x32_bf16 v[4:7], v[156:159], v[88:91], 0
	ds_read_b128 v[176:179], v36 offset:20544
	s_waitcnt lgkmcnt(4)
	v_mfma_f32_16x16x32_bf16 v[84:87], v[160:163], v[92:95], v[4:7]
	ds_read_b128 v[156:159], v36 offset:23040
	s_waitcnt lgkmcnt(4)
	v_mfma_f32_16x16x32_bf16 v[4:7], v[164:167], v[88:91], 0
	ds_read_b128 v[160:163], v36 offset:23104
	s_waitcnt lgkmcnt(4)
	v_mfma_f32_16x16x32_bf16 v[32:35], v[168:171], v[92:95], v[4:7]
	ds_read_b128 v[164:167], v36 offset:25600
	s_waitcnt lgkmcnt(4)
	v_mfma_f32_16x16x32_bf16 v[4:7], v[172:175], v[88:91], 0
	ds_read_b128 v[168:171], v36 offset:25664
	s_waitcnt lgkmcnt(4)
	v_mfma_f32_16x16x32_bf16 v[28:31], v[176:179], v[92:95], v[4:7]
	ds_read_b128 v[172:175], v36 offset:28160
	s_waitcnt lgkmcnt(4)
	v_mfma_f32_16x16x32_bf16 v[4:7], v[156:159], v[88:91], 0
	ds_read_b128 v[176:179], v36 offset:28224
	s_waitcnt lgkmcnt(4)
	v_mfma_f32_16x16x32_bf16 v[24:27], v[160:163], v[92:95], v[4:7]
	ds_read_b128 v[156:159], v36 offset:30720
	s_waitcnt lgkmcnt(4)
	v_mfma_f32_16x16x32_bf16 v[4:7], v[164:167], v[88:91], 0
	ds_read_b128 v[160:163], v36 offset:30784
	s_waitcnt lgkmcnt(4)
	v_mfma_f32_16x16x32_bf16 v[20:23], v[168:171], v[92:95], v[4:7]
	ds_read_b128 v[164:167], v36 offset:33280
	s_waitcnt lgkmcnt(4)
	v_mfma_f32_16x16x32_bf16 v[4:7], v[172:175], v[88:91], 0
	ds_read_b128 v[168:171], v36 offset:33344
	s_waitcnt lgkmcnt(4)
	v_mfma_f32_16x16x32_bf16 v[16:19], v[176:179], v[92:95], v[4:7]
	ds_read_b128 v[172:175], v36 offset:35840
	s_waitcnt lgkmcnt(4)
	v_mfma_f32_16x16x32_bf16 v[4:7], v[156:159], v[88:91], 0
	ds_read_b128 v[176:179], v36 offset:35904
	s_waitcnt lgkmcnt(4)
	v_mfma_f32_16x16x32_bf16 v[12:15], v[160:163], v[92:95], v[4:7]
	ds_read_b128 v[156:159], v36 offset:38400
	s_waitcnt lgkmcnt(4)
	v_mfma_f32_16x16x32_bf16 v[4:7], v[164:167], v[88:91], 0
	ds_read_b128 v[160:163], v36 offset:38464
	s_waitcnt lgkmcnt(4)
	v_mfma_f32_16x16x32_bf16 v[8:11], v[168:171], v[92:95], v[4:7]
	s_waitcnt lgkmcnt(3)
	v_mfma_f32_16x16x32_bf16 v[4:7], v[172:175], v[88:91], 0
	s_waitcnt lgkmcnt(2)
	v_mfma_f32_16x16x32_bf16 v[4:7], v[176:179], v[92:95], v[4:7]
	v_max3_f32 v36, v60, s20, v61
	v_max_f32_e32 v44, v62, v63
	v_max_f32_e32 v59, v64, v65
	v_max_f32_e32 v152, v66, v67
	v_max3_f32 v36, v36, v68, v69
	v_max3_f32 v44, v44, v70, v71
	v_max3_f32 v59, v59, v72, v73
	v_max3_f32 v152, v152, v74, v75
	v_max3_f32 v36, v36, v76, v77
	v_max3_f32 v44, v44, v78, v79
	v_max3_f32 v59, v59, v80, v81
	v_max3_f32 v152, v152, v82, v83
	v_max3_f32 v36, v36, v84, v85
	v_max3_f32 v44, v44, v86, v87
	v_max3_f32 v59, v59, v32, v33
	v_max3_f32 v152, v152, v34, v35
	v_max3_f32 v36, v36, v28, v29
	v_max3_f32 v44, v44, v30, v31
	v_max3_f32 v59, v59, v24, v25
	v_max3_f32 v152, v152, v26, v27
	v_max3_f32 v36, v36, v20, v21
	s_waitcnt lgkmcnt(1)
	v_mfma_f32_16x16x32_bf16 v[88:91], v[156:159], v[88:91], 0
	v_max3_f32 v44, v44, v22, v23
	v_max3_f32 v59, v59, v16, v17
	v_max3_f32 v152, v152, v18, v19
	v_max3_f32 v36, v36, v12, v13
	s_waitcnt lgkmcnt(0)
	v_mfma_f32_16x16x32_bf16 v[0:3], v[160:163], v[92:95], v[88:91]
	v_max3_f32 v44, v44, v14, v15
	v_max3_f32 v59, v59, v8, v9
	v_max3_f32 v152, v152, v10, v11
	v_max3_f32 v36, v36, v4, v5
	v_max3_f32 v44, v44, v6, v7
	s_nop 2
	v_max3_f32 v59, v59, v0, v1
	v_max3_f32 v152, v152, v2, v3
	v_max3_f32 v36, v36, v44, v59
	v_max_f32_e32 v36, v36, v152
	v_mul_f32_e32 v36, 0x3e38aa3b, v36
	v_max_f32_e32 v36, s20, v36
	v_cndmask_b32_e32 v44, v48, v49, vcc
	v_lshlrev_b32_e32 v88, 2, v44
	ds_bpermute_b32 v44, v88, v36
	v_cmp_lt_i32_e32 vcc, v51, v50
	s_waitcnt lgkmcnt(0)
	s_barrier
	v_max_f32_e32 v44, v44, v44
	v_max_f32_e32 v36, v36, v44
	v_cndmask_b32_e32 v44, v48, v51, vcc
	v_lshlrev_b32_e32 v89, 2, v44
	ds_bpermute_b32 v59, v89, v36
	v_lshlrev_b32_e32 v44, 3, v57
	s_waitcnt lgkmcnt(0)
	v_max_f32_e32 v59, v59, v59
	v_max_f32_e32 v36, v36, v59
	v_fma_f32 v59, v60, s19, -v36
	v_fma_f32 v60, v61, s19, -v36
	v_fma_f32 v61, v62, s19, -v36
	v_fma_f32 v63, v63, s19, -v36
	v_fma_f32 v64, v64, s19, -v36
	v_fma_f32 v65, v65, s19, -v36
	v_fma_f32 v66, v66, s19, -v36
	v_fma_f32 v67, v67, s19, -v36
	v_fma_f32 v32, v32, s19, -v36
	v_fma_f32 v0, v0, s19, -v36
	v_exp_f32_e32 v59, v59
	v_exp_f32_e32 v60, v60
	v_exp_f32_e32 v61, v61
	v_exp_f32_e32 v63, v63
	v_exp_f32_e32 v64, v64
	v_exp_f32_e32 v65, v65
	v_exp_f32_e32 v66, v66
	v_exp_f32_e32 v67, v67
	v_fma_f32 v68, v68, s19, -v36
	v_fma_f32 v69, v69, s19, -v36
	v_fma_f32 v70, v70, s19, -v36
	v_fma_f32 v71, v71, s19, -v36
	v_fma_f32 v72, v72, s19, -v36
	v_fma_f32 v73, v73, s19, -v36
	v_fma_f32 v74, v74, s19, -v36
	v_fma_f32 v75, v75, s19, -v36
	v_exp_f32_e32 v91, v32
	v_fma_f32 v32, v33, s19, -v36
	v_fma_f32 v28, v28, s19, -v36
	v_fma_f32 v24, v24, s19, -v36
	v_fma_f32 v4, v4, s19, -v36
	v_exp_f32_e32 v123, v0
	v_fma_f32 v0, v1, s19, -v36
	v_ashrrev_i32_e32 v62, 2, v58
	v_exp_f32_e32 v68, v68
	v_exp_f32_e32 v69, v69
	v_exp_f32_e32 v70, v70
	v_exp_f32_e32 v71, v71
	v_exp_f32_e32 v72, v72
	v_exp_f32_e32 v73, v73
	v_exp_f32_e32 v74, v74
	v_exp_f32_e32 v75, v75
	v_fma_f32 v76, v76, s19, -v36
	v_fma_f32 v77, v77, s19, -v36
	v_fma_f32 v78, v78, s19, -v36
	v_fma_f32 v79, v79, s19, -v36
	v_fma_f32 v80, v80, s19, -v36
	v_fma_f32 v81, v81, s19, -v36
	v_fma_f32 v82, v82, s19, -v36
	v_fma_f32 v83, v83, s19, -v36
	v_exp_f32_e32 v92, v32
	v_fma_f32 v32, v34, s19, -v36
	v_exp_f32_e32 v95, v28
	v_fma_f32 v28, v29, s19, -v36
	v_exp_f32_e32 v99, v24
	v_fma_f32 v24, v25, s19, -v36
	v_fma_f32 v20, v20, s19, -v36
	v_fma_f32 v16, v16, s19, -v36
	v_exp_f32_e32 v119, v4
	v_fma_f32 v4, v5, s19, -v36
	v_exp_f32_e32 v124, v0
	v_fma_f32 v0, v2, s19, -v36
	v_exp_f32_e32 v76, v76
	v_exp_f32_e32 v77, v77
	v_exp_f32_e32 v78, v78
	v_exp_f32_e32 v79, v79
	v_exp_f32_e32 v80, v80
	v_exp_f32_e32 v81, v81
	v_exp_f32_e32 v82, v82
	v_exp_f32_e32 v83, v83
	v_fma_f32 v84, v84, s19, -v36
	v_fma_f32 v85, v85, s19, -v36
	v_fma_f32 v86, v86, s19, -v36
	v_fma_f32 v87, v87, s19, -v36
	v_exp_f32_e32 v93, v32
	v_fma_f32 v32, v35, s19, -v36
	v_exp_f32_e32 v96, v28
	v_fma_f32 v28, v30, s19, -v36
	v_exp_f32_e32 v100, v24
	v_fma_f32 v24, v26, s19, -v36
	v_exp_f32_e32 v103, v20
	v_fma_f32 v20, v21, s19, -v36
	v_exp_f32_e32 v107, v16
	v_fma_f32 v16, v17, s19, -v36
	v_fma_f32 v12, v12, s19, -v36
	v_fma_f32 v8, v8, s19, -v36
	v_exp_f32_e32 v120, v4
	v_fma_f32 v4, v6, s19, -v36
	v_exp_f32_e32 v125, v0
	v_fma_f32 v0, v3, s19, -v36
	v_bfi_b32 v127, -16, v62, v58
	v_exp_f32_e32 v84, v84
	v_exp_f32_e32 v85, v85
	v_exp_f32_e32 v86, v86
	v_exp_f32_e32 v87, v87
	v_exp_f32_e32 v94, v32
	v_exp_f32_e32 v97, v28
	v_fma_f32 v28, v31, s19, -v36
	v_exp_f32_e32 v101, v24
	v_fma_f32 v24, v27, s19, -v36
	v_exp_f32_e32 v104, v20
	v_fma_f32 v20, v22, s19, -v36
	v_exp_f32_e32 v108, v16
	v_fma_f32 v16, v18, s19, -v36
	v_exp_f32_e32 v111, v12
	v_fma_f32 v12, v13, s19, -v36
	v_exp_f32_e32 v115, v8
	v_fma_f32 v8, v9, s19, -v36
	v_exp_f32_e32 v121, v4
	v_fma_f32 v4, v7, s19, -v36
	v_exp_f32_e32 v126, v0
	v_mul_lo_u32 v0, v127, s18
	v_exp_f32_e32 v98, v28
	v_exp_f32_e32 v102, v24
	v_exp_f32_e32 v105, v20
	v_fma_f32 v20, v23, s19, -v36
	v_exp_f32_e32 v109, v16
	v_fma_f32 v16, v19, s19, -v36
	v_exp_f32_e32 v112, v12
	v_fma_f32 v12, v14, s19, -v36
	v_exp_f32_e32 v116, v8
	v_fma_f32 v8, v10, s19, -v36
	v_exp_f32_e32 v122, v4
	v_or_b32_e32 v4, v0, v44
	v_cvt_pk_bf16_f32 v0, v59, v60
	v_cvt_pk_bf16_f32 v1, v61, v63
	v_cvt_pk_bf16_f32 v2, v64, v65
	v_cvt_pk_bf16_f32 v3, v66, v67
	v_exp_f32_e32 v106, v20
	v_exp_f32_e32 v110, v16
	v_exp_f32_e32 v113, v12
	v_fma_f32 v12, v15, s19, -v36
	v_exp_f32_e32 v117, v8
	v_fma_f32 v8, v11, s19, -v36
	ds_write2_b64 v4, v[0:1], v[2:3] offset1:4
	v_cvt_pk_bf16_f32 v0, v68, v69
	v_cvt_pk_bf16_f32 v1, v70, v71
	v_cvt_pk_bf16_f32 v2, v72, v73
	v_cvt_pk_bf16_f32 v3, v74, v75
	v_exp_f32_e32 v114, v12
	v_exp_f32_e32 v118, v8
	ds_write2_b64 v4, v[0:1], v[2:3] offset0:8 offset1:12
	v_cvt_pk_bf16_f32 v0, v76, v77
	v_cvt_pk_bf16_f32 v1, v78, v79
	v_cvt_pk_bf16_f32 v2, v80, v81
	v_cvt_pk_bf16_f32 v3, v82, v83
	ds_write2_b64 v4, v[0:1], v[2:3] offset0:16 offset1:20
	v_cvt_pk_bf16_f32 v0, v84, v85
	v_cvt_pk_bf16_f32 v1, v86, v87
	v_cvt_pk_bf16_f32 v2, v91, v92
	v_cvt_pk_bf16_f32 v3, v93, v94
	ds_write2_b64 v4, v[0:1], v[2:3] offset0:24 offset1:28
	v_cvt_pk_bf16_f32 v0, v95, v96
	v_cvt_pk_bf16_f32 v1, v97, v98
	v_cvt_pk_bf16_f32 v2, v99, v100
	v_cvt_pk_bf16_f32 v3, v101, v102
	v_add_f32_e32 v90, 0, v59
	ds_write2_b64 v4, v[0:1], v[2:3] offset0:32 offset1:36
	v_cvt_pk_bf16_f32 v0, v103, v104
	v_cvt_pk_bf16_f32 v1, v105, v106
	v_cvt_pk_bf16_f32 v2, v107, v108
	v_cvt_pk_bf16_f32 v3, v109, v110
	v_add_f32_e32 v90, v60, v90
	ds_write2_b64 v4, v[0:1], v[2:3] offset0:40 offset1:44
	v_cvt_pk_bf16_f32 v0, v111, v112
	v_cvt_pk_bf16_f32 v1, v113, v114
	v_cvt_pk_bf16_f32 v2, v115, v116
	v_cvt_pk_bf16_f32 v3, v117, v118
	v_add_f32_e32 v90, v61, v90
	ds_write2_b64 v4, v[0:1], v[2:3] offset0:48 offset1:52
	v_cvt_pk_bf16_f32 v0, v119, v120
	v_cvt_pk_bf16_f32 v1, v121, v122
	v_cvt_pk_bf16_f32 v2, v123, v124
	v_cvt_pk_bf16_f32 v3, v125, v126
	v_add_f32_e32 v90, v63, v90
	ds_write2_b64 v4, v[0:1], v[2:3] offset0:56 offset1:60
	ds_read_b128 v[0:3], v42 offset:40960
	v_add_f32_e32 v90, v64, v90
	v_add_f32_e32 v90, v65, v90
	v_add_f32_e32 v90, v66, v90
	v_add_f32_e32 v12, v67, v90
	v_add_u32_e32 v43, v4, v44
	ds_read_b128 v[4:7], v43
	ds_read_b128 v[8:11], v42 offset:49664
	v_add_f32_e32 v32, v68, v12
	v_add_u32_e32 v66, 0x2200, v42
	ds_read_b128 v[12:15], v42 offset:58368
	ds_read_b128 v[16:19], v43 offset:64
	ds_read_b128 v[20:23], v42 offset:41024
	ds_read_b128 v[24:27], v66 offset:58368
	ds_read_b128 v[28:31], v42 offset:49728
	v_add_f32_e32 v32, v69, v32
	v_add_f32_e32 v58, v70, v32
	v_add_f32_e32 v58, v71, v58
	s_waitcnt lgkmcnt(6)
	v_mfma_f32_16x16x32_bf16 v[0:3], v[0:3], v[4:7], 0
	v_add_f32_e32 v62, v72, v58
	ds_read_b128 v[32:35], v42 offset:58432
	ds_read_b128 v[58:61], v66 offset:58432
	s_waitcnt lgkmcnt(7)
	v_mfma_f32_16x16x32_bf16 v[8:11], v[8:11], v[4:7], 0
	s_waitcnt lgkmcnt(6)
	v_mfma_f32_16x16x32_bf16 v[12:15], v[12:15], v[4:7], 0
	s_waitcnt lgkmcnt(3)
	v_mfma_f32_16x16x32_bf16 v[4:7], v[24:27], v[4:7], 0
	v_add_f32_e32 v24, v73, v62
	v_add_f32_e32 v24, v74, v24
	v_add_f32_e32 v24, v75, v24
	v_mfma_f32_16x16x32_bf16 v[0:3], v[20:23], v[16:19], v[0:3]
	v_add_f32_e32 v20, v76, v24
	v_add_f32_e32 v20, v77, v20
	v_add_f32_e32 v20, v78, v20
	v_add_f32_e32 v20, v79, v20
	v_add_f32_e32 v24, v80, v20
	ds_read_b128 v[20:23], v42 offset:41088
	s_waitcnt lgkmcnt(3)
	v_mfma_f32_16x16x32_bf16 v[8:11], v[28:31], v[16:19], v[8:11]
	v_add_f32_e32 v62, v81, v24
	ds_read_b128 v[24:27], v43 offset:128
	ds_read_b128 v[28:31], v42 offset:49792
	v_add_f32_e32 v67, v82, v62
	s_waitcnt lgkmcnt(4)
	v_mfma_f32_16x16x32_bf16 v[12:15], v[32:35], v[16:19], v[12:15]
	s_waitcnt lgkmcnt(3)
	v_mfma_f32_16x16x32_bf16 v[4:7], v[58:61], v[16:19], v[4:7]
	ds_read_b128 v[16:19], v42 offset:58496
	ds_read_b128 v[32:35], v43 offset:192
	ds_read_b128 v[58:61], v42 offset:41152
	s_waitcnt lgkmcnt(4)
	v_mfma_f32_16x16x32_bf16 v[0:3], v[20:23], v[24:27], v[0:3]
	ds_read_b128 v[20:23], v66 offset:58496
	ds_read_b128 v[62:65], v42 offset:49856
	s_waitcnt lgkmcnt(5)
	v_mfma_f32_16x16x32_bf16 v[8:11], v[28:31], v[24:27], v[8:11]
	v_add_f32_e32 v28, v83, v67
	v_add_f32_e32 v67, v84, v28
	ds_read_b128 v[28:31], v42 offset:58560
	s_waitcnt lgkmcnt(5)
	v_mfma_f32_16x16x32_bf16 v[12:15], v[16:19], v[24:27], v[12:15]
	v_add_f32_e32 v16, v85, v67
	v_add_f32_e32 v67, v86, v16
	ds_read_b128 v[16:19], v66 offset:58560
	s_waitcnt lgkmcnt(3)
	v_mfma_f32_16x16x32_bf16 v[4:7], v[20:23], v[24:27], v[4:7]
	v_add_f32_e32 v20, v87, v67
	v_add_f32_e32 v20, v91, v20
	v_add_f32_e32 v20, v92, v20
	v_add_f32_e32 v20, v93, v20
	v_add_f32_e32 v20, v94, v20
	v_add_f32_e32 v20, v95, v20
	v_add_f32_e32 v20, v96, v20
	v_add_f32_e32 v24, v97, v20
	ds_read_b128 v[20:23], v42 offset:41216
	s_waitcnt lgkmcnt(3)
	v_mfma_f32_16x16x32_bf16 v[8:11], v[62:65], v[32:35], v[8:11]
	v_add_f32_e32 v62, v98, v24
	v_add_f32_e32 v67, v99, v62
	s_waitcnt lgkmcnt(2)
	v_mfma_f32_16x16x32_bf16 v[12:15], v[28:31], v[32:35], v[12:15]
	ds_read_b128 v[24:27], v43 offset:256
	ds_read_b128 v[28:31], v42 offset:49920
	v_mfma_f32_16x16x32_bf16 v[0:3], v[58:61], v[32:35], v[0:3]
	s_waitcnt lgkmcnt(3)
	v_mfma_f32_16x16x32_bf16 v[4:7], v[16:19], v[32:35], v[4:7]
	ds_read_b128 v[16:19], v42 offset:58624
	ds_read_b128 v[32:35], v43 offset:320
	ds_read_b128 v[58:61], v42 offset:41280
	s_waitcnt lgkmcnt(4)
	v_mfma_f32_16x16x32_bf16 v[0:3], v[20:23], v[24:27], v[0:3]
	ds_read_b128 v[20:23], v66 offset:58624
	ds_read_b128 v[62:65], v42 offset:49984
	s_waitcnt lgkmcnt(5)
	v_mfma_f32_16x16x32_bf16 v[8:11], v[28:31], v[24:27], v[8:11]
	v_add_f32_e32 v28, v100, v67
	v_add_f32_e32 v67, v101, v28
	ds_read_b128 v[28:31], v42 offset:58688
	s_waitcnt lgkmcnt(5)
	v_mfma_f32_16x16x32_bf16 v[12:15], v[16:19], v[24:27], v[12:15]
	v_add_f32_e32 v16, v102, v67
	v_add_f32_e32 v67, v103, v16
	ds_read_b128 v[16:19], v66 offset:58688
	s_waitcnt lgkmcnt(3)
	v_mfma_f32_16x16x32_bf16 v[4:7], v[20:23], v[24:27], v[4:7]
	v_add_f32_e32 v20, v104, v67
	v_add_f32_e32 v20, v105, v20
	v_add_f32_e32 v20, v106, v20
	v_add_f32_e32 v20, v107, v20
	v_add_f32_e32 v20, v108, v20
	v_add_f32_e32 v20, v109, v20
	v_add_f32_e32 v20, v110, v20
	v_add_f32_e32 v24, v111, v20
	ds_read_b128 v[20:23], v42 offset:41344
	s_waitcnt lgkmcnt(3)
	v_mfma_f32_16x16x32_bf16 v[8:11], v[62:65], v[32:35], v[8:11]
	v_add_f32_e32 v62, v112, v24
	s_waitcnt lgkmcnt(2)
	v_mfma_f32_16x16x32_bf16 v[12:15], v[28:31], v[32:35], v[12:15]
	ds_read_b128 v[24:27], v43 offset:384
	ds_read_b128 v[28:31], v42 offset:50048
	v_mfma_f32_16x16x32_bf16 v[0:3], v[58:61], v[32:35], v[0:3]
	s_waitcnt lgkmcnt(3)
	v_mfma_f32_16x16x32_bf16 v[4:7], v[16:19], v[32:35], v[4:7]
	ds_read_b128 v[16:19], v42 offset:58752
	ds_read_b128 v[32:35], v43 offset:448
	ds_read_b128 v[58:61], v42 offset:41408
	v_add_f32_e32 v43, v113, v62
	s_waitcnt lgkmcnt(4)
	v_mfma_f32_16x16x32_bf16 v[0:3], v[20:23], v[24:27], v[0:3]
	ds_read_b128 v[20:23], v66 offset:58752
	ds_read_b128 v[62:65], v42 offset:50112
	ds_read_b128 v[66:69], v66 offset:58816
	s_waitcnt lgkmcnt(6)
	v_mfma_f32_16x16x32_bf16 v[8:11], v[28:31], v[24:27], v[8:11]
	v_add_f32_e32 v28, v114, v43
	v_add_f32_e32 v43, v115, v28
	ds_read_b128 v[28:31], v42 offset:58816
	s_waitcnt lgkmcnt(6)
	v_mfma_f32_16x16x32_bf16 v[16:19], v[16:19], v[24:27], v[12:15]
	s_nop 2
	v_add_f32_e32 v12, v116, v43
	v_add_f32_e32 v12, v117, v12
	s_waitcnt lgkmcnt(3)
	v_mfma_f32_16x16x32_bf16 v[20:23], v[20:23], v[24:27], v[4:7]
	s_nop 2
	v_add_f32_e32 v4, v118, v12
	v_add_f32_e32 v4, v119, v4
	v_add_f32_e32 v4, v120, v4
	v_mfma_f32_16x16x32_bf16 v[12:15], v[58:61], v[32:35], v[0:3]
	s_nop 2
	v_add_f32_e32 v0, v121, v4
	v_add_f32_e32 v0, v122, v0
	v_add_f32_e32 v0, v123, v0
	v_add_f32_e32 v0, v124, v0
	v_add_f32_e32 v0, v125, v0
	v_add_f32_e32 v0, v126, v0
	ds_bpermute_b32 v1, v88, v0
	s_waitcnt lgkmcnt(1)
	v_mfma_f32_16x16x32_bf16 v[4:7], v[28:31], v[32:35], v[16:19]
	s_waitcnt lgkmcnt(0)
	s_nop 1
	v_add_f32_e32 v16, v0, v1
	ds_bpermute_b32 v17, v89, v16
	v_mfma_f32_16x16x32_bf16 v[8:11], v[62:65], v[32:35], v[8:11]
	v_add_u32_e32 v18, v127, v55
	v_cmp_lt_i32_e32 vcc, v18, v45
	v_mfma_f32_16x16x32_bf16 v[0:3], v[66:69], v[32:35], v[20:23]
	s_and_saveexec_b64 s[14:15], vcc
	s_cbranch_execz .LBB0_1469
	s_waitcnt lgkmcnt(0)
	v_add_f32_e32 v17, v16, v17
	v_div_scale_f32 v16, s[22:23], v17, v17, 1.0
	v_rcp_f32_e32 v18, v16
	v_div_scale_f32 v19, vcc, 1.0, v17, 1.0
	s_lshl_b64 s[12:13], s[12:13], 17
	v_fma_f32 v20, -v16, v18, 1.0
	v_fmac_f32_e32 v18, v20, v18
	v_mul_f32_e32 v20, v19, v18
	v_fma_f32 v21, -v16, v20, v19
	v_fmac_f32_e32 v20, v21, v18
	v_fma_f32 v16, -v16, v20, v19
	v_div_fmas_f32 v16, v16, v18, v20
	s_lshl_b32 s11, s11, 2
	v_bfe_u32 v20, v53, 2, 2
	v_lshl_add_u64 v[18:19], v[40:41], 3, s[12:13]
	v_div_fixup_f32 v16, v16, v17, 1.0
	v_or3_b32 v18, v18, v20, s11
	v_lshlrev_b64 v[18:19], 2, v[18:19]
	v_pk_mul_f32 v[12:13], v[16:17], v[12:13] op_sel_hi:[0,1]
	v_and_or_b32 v18, v53, 3, v18
	v_cvt_pk_bf16_f32 v20, v12, v13
	v_pk_mul_f32 v[12:13], v[16:17], v[14:15] op_sel_hi:[0,1]
	v_readlane_b32 s12, v237, 40
	v_cvt_pk_bf16_f32 v21, v12, v13
	v_lshlrev_b64 v[12:13], 7, v[18:19]
	v_readlane_b32 s13, v237, 41
	v_mov_b32_e32 v45, v37
	v_cmp_eq_u32_e32 vcc, 0, v57
	v_lshl_add_u64 v[12:13], s[12:13], 0, v[12:13]
	v_lshl_add_u64 v[12:13], v[12:13], 0, v[44:45]
	global_store_dwordx2 v[12:13], v[20:21], off
	s_and_saveexec_b64 s[12:13], vcc
	s_cbranch_execz .LBB0_1468
	v_lshlrev_b64 v[14:15], 2, v[18:19]
	v_mul_f32_e32 v20, 0x3f317218, v36
	v_lshl_add_u64 v[18:19], s[2:3], 0, v[14:15]
	v_lshl_add_u64 v[14:15], s[8:9], 0, v[14:15]
	global_store_dword v[18:19], v20, off
	global_store_dword v[14:15], v17, off
	s_branch .LBB0_1468
